# defer 13440 w_down conversion items from P0 into the idle tail of P1 (WGs>=116 re-enter the conversion loop after their PLE GEMM)
# speedup vs baseline: 1.0162x; 1.0162x over previous
.LBB0_6:
	s_or_b64 exec, exec, s[0:1]
	s_lshr_b32 s1, s91, 6
	s_lshl_b32 s0, s90, 3
	v_writelane_b32 v250, s1, 9
	s_add_i32 s12, s0, s1
	s_lshl_b32 s14, s88, 3
	s_cmpk_lg_i32 s88, 0x100
	s_cselect_b32 s101, 2, 0
	s_mov_b32 s100, 0x1ad00
.Lcv_entry:
	s_mov_b64 s[0:1], s[86:87]
	s_cmp_lt_i32 s12, s100
	v_mbcnt_lo_u32_b32 v64, -1, 0
	v_mbcnt_hi_u32_b32 v64, -1, v64
	s_nop 0
	s_cbranch_scc0 .LBB0_37
	v_readlane_b32 s3, v250, 9
	s_lshl_b32 s3, s3, 14
	v_and_b32_e32 v65, 31, v64
	v_ashrrev_i32_e32 v74, 5, v64
	s_movk_i32 s4, 0x84
	s_add_i32 s3, s3, 0
	v_lshlrev_b32_e32 v0, 2, v65
	v_mul_lo_u32 v1, v74, s4
	v_add3_u32 v75, s3, v0, v1
	v_lshlrev_b32_e32 v0, 3, v64
	v_ashrrev_i32_e32 v76, 3, v64
	v_and_b32_e32 v66, 56, v0
	v_mul_u32_u24_e32 v0, 0x84, v66
	v_lshlrev_b32_e32 v1, 2, v76
	v_mov_b32_e32 v69, 0
	v_add3_u32 v77, s3, v0, v1
	v_lshlrev_b32_e32 v0, 2, v64
	v_mov_b32_e32 v67, v69
	v_add_u32_e32 v78, 8, v76
	v_add_u32_e32 v79, 16, v76
	v_add_u32_e32 v80, 24, v76
	v_xor_b32_e32 v81, 0x80, v0
	s_lshl_b32 s3, s12, 5
	s_lshl_b32 s13, s14, 5
	s_lshl_b32 s15, s12, 3
	s_lshl_b32 s33, s14, 3
	s_mov_b32 s34, 0x8000
	s_movk_i32 s35, 0x7fff
	s_mov_b32 s36, 0xffff0000
	s_mov_b32 s37, 0x10000
	s_mov_b32 s38, 0x18000
	s_mov_b32 s39, 0x20000
	s_mov_b32 s40, 0x28000
	s_mov_b32 s41, 0x30000
	s_mov_b32 s42, 0x38000
	s_mov_b32 s43, 0x40000
	s_mov_b32 s44, 0x48000
	s_mov_b32 s45, 0x50000
	s_mov_b32 s46, 0x58000
	s_mov_b32 s47, 0x60000
	s_mov_b32 s48, 0x68000
	s_mov_b32 s49, 0x70000
	s_mov_b32 s50, 0x78000
	s_mov_b32 s51, 0x80000
	s_mov_b32 s52, 0x88000
	s_mov_b32 s53, 0x90000
	s_mov_b32 s54, 0x98000
	s_mov_b32 s55, 0xa0000
	s_mov_b32 s56, 0xa8000
	s_mov_b32 s57, 0xb0000
	s_mov_b32 s58, 0xb8000
	s_mov_b32 s59, 0xc0000
	s_mov_b32 s60, 0xc8000
	s_mov_b32 s61, 0xd0000
	s_mov_b32 s62, 0xd8000
	s_mov_b32 s63, 0xe0000
	s_mov_b32 s64, 0xe8000
	s_mov_b32 s65, 0xf0000
	s_mov_b32 s66, 0xf8000
	s_movk_i32 s67, 0x2b00
	v_add_u32_e32 v82, 0x400, v75
	v_add_u32_e32 v83, 0x800, v75
	v_add_u32_e32 v84, 0xc00, v75
	v_add_u32_e32 v85, 0x1000, v75
	v_add_u32_e32 v86, 0x1400, v75
	v_add_u32_e32 v87, 0x1800, v75
	v_add_u32_e32 v88, 0x1c00, v75
	v_lshlrev_b32_e32 v70, 1, v66
	v_mov_b32_e32 v89, 0x80
	v_mov_b32_e32 v90, 0x42fe0000
	s_movk_i32 s68, 0x2aff
	s_mov_b32 s69, 0xc2fe0000
	s_mov_b32 s70, 0xc0c0500
	s_mov_b32 s71, 0x258000
	s_mov_b32 s72, 0x272000
	s_mov_b32 s73, 0x28c000
	s_mov_b32 s74, 0x2a6000
	s_mov_b32 s75, 0x2c0000
	s_mov_b32 s76, 0x2da000
	s_mov_b32 s77, 0x2f4000
	s_mov_b32 s78, 0x30e000
	s_mov_b32 s79, 0x328000
	s_mov_b32 s80, s12
	s_mov_b32 s17, 0
	v_cmp_gt_u32_e64 s[4:5], 32, v64
	s_mov_b64 s[18:19], 0x1f700000
	s_mov_b64 s[20:21], 0x1f500000
	s_mov_b64 s[22:23], 0x17f00000
	s_mov_b64 s[24:25], 0xd300000
	s_mov_b64 s[26:27], 0x1d500000
	s_mov_b64 s[28:29], 0xb300000
	s_mov_b64 s[30:31], 0x100000
	s_branch .LBB0_9
.LBB0_8:
	s_add_i32 s80, s80, s14
	s_add_i32 s3, s3, s13
	s_add_i32 s15, s15, s33
	s_cmp_ge_i32 s80, s100
	s_cbranch_scc1 .LBB0_37
.LBB0_9:
	s_cmp_lg_u32 s101, 0
	s_cbranch_scc1 .Lcv_go
	s_cmp_lt_i32 s80, 0x17600
	s_cbranch_scc1 .Lcv_go
	s_cmp_lt_i32 s80, 0x1aa80
	s_cbranch_scc1 .LBB0_8

.LBB0_37:
	s_cmp_eq_u32 s101, 1
	s_cbranch_scc1 .Lcv_return
	s_load_dwordx2 s[4:5], s[0:1], 0xc0
	s_and_b32 s64, s91, 0xffffffc0
	s_lshl_b32 s3, s2, 9
	s_add_i32 s6, s64, s3
	v_writelane_b32 v250, s6, 12
	v_add_u32_e32 v4, s6, v64
	s_mov_b32 s6, 0x18000
	s_lshl_b32 s92, s88, 9
	v_cmp_gt_i32_e32 vcc, s6, v4
	s_and_saveexec_b64 s[6:7], vcc
	s_cbranch_execz .LBB0_40
	v_ashrrev_i32_e32 v5, 31, v4
	s_waitcnt lgkmcnt(0)
	v_lshl_add_u64 v[0:1], v[4:5], 4, s[4:5]
	s_mov_b64 s[8:9], 0x6980000
	v_lshl_add_u64 v[6:7], v[0:1], 0, s[8:9]
	s_ashr_i32 s93, s92, 31
	v_mov_b32_e32 v0, 0
	s_lshl_b64 s[8:9], s[92:93], 4
	s_mov_b64 s[10:11], 0
	v_mov_b32_e32 v1, v0
	v_mov_b32_e32 v2, v0
	v_mov_b32_e32 v3, v0
	s_mov_b32 s13, 0x17fff
	v_mov_b32_e32 v5, v4

.LBB0_415:
	s_waitcnt vmcnt(0)
	s_barrier
	v_writelane_b32 v248, s0, 0
	v_writelane_b32 v248, s1, 1
	v_writelane_b32 v248, s2, 2
	v_writelane_b32 v248, s3, 3
	v_writelane_b32 v248, s4, 4
	v_writelane_b32 v248, s5, 5
	v_writelane_b32 v248, s6, 6
	v_writelane_b32 v248, s7, 7
	v_writelane_b32 v248, s8, 8
	v_writelane_b32 v248, s9, 9
	v_writelane_b32 v248, s10, 10
	v_writelane_b32 v248, s11, 11
	v_writelane_b32 v248, s12, 12
	v_writelane_b32 v248, s13, 13
	v_writelane_b32 v248, s14, 14
	v_writelane_b32 v248, s15, 15
	v_writelane_b32 v248, s16, 16
	v_writelane_b32 v248, s17, 17
	v_writelane_b32 v248, s18, 18
	v_writelane_b32 v248, s19, 19
	v_writelane_b32 v248, s20, 20
	v_writelane_b32 v248, s21, 21
	v_writelane_b32 v248, s22, 22
	v_writelane_b32 v248, s23, 23
	v_writelane_b32 v248, s24, 24
	v_writelane_b32 v248, s25, 25
	v_writelane_b32 v248, s26, 26
	v_writelane_b32 v248, s27, 27
	v_writelane_b32 v248, s28, 28
	v_writelane_b32 v248, s29, 29
	v_writelane_b32 v248, s30, 30
	v_writelane_b32 v248, s31, 31
	v_writelane_b32 v248, s32, 32
	v_writelane_b32 v248, s33, 33
	v_writelane_b32 v248, s34, 34
	v_writelane_b32 v248, s35, 35
	v_writelane_b32 v248, s36, 36
	v_writelane_b32 v248, s37, 37
	v_writelane_b32 v248, s38, 38
	v_writelane_b32 v248, s39, 39
	v_writelane_b32 v248, s40, 40
	v_writelane_b32 v248, s41, 41
	v_writelane_b32 v248, s42, 42
	v_writelane_b32 v248, s43, 43
	v_writelane_b32 v248, s44, 44
	v_writelane_b32 v248, s45, 45
	v_writelane_b32 v248, s46, 46
	v_writelane_b32 v248, s47, 47
	v_writelane_b32 v248, s48, 48
	v_writelane_b32 v248, s49, 49
	v_writelane_b32 v248, s50, 50
	v_writelane_b32 v248, s51, 51
	v_writelane_b32 v248, s52, 52
	v_writelane_b32 v248, s53, 53
	v_writelane_b32 v248, s54, 54
	v_writelane_b32 v248, s55, 55
	v_writelane_b32 v248, s56, 56
	v_writelane_b32 v248, s57, 57
	v_writelane_b32 v248, s58, 58
	v_writelane_b32 v248, s59, 59
	v_writelane_b32 v248, s60, 60
	v_writelane_b32 v248, s61, 61
	v_writelane_b32 v248, s62, 62
	v_writelane_b32 v248, s63, 63
	v_writelane_b32 v249, s64, 0
	v_writelane_b32 v249, s65, 1
	v_writelane_b32 v249, s66, 2
	v_writelane_b32 v249, s67, 3
	v_writelane_b32 v249, s68, 4
	v_writelane_b32 v249, s69, 5
	v_writelane_b32 v249, s70, 6
	v_writelane_b32 v249, s71, 7
	v_writelane_b32 v249, s72, 8
	v_writelane_b32 v249, s73, 9
	v_writelane_b32 v249, s74, 10
	v_writelane_b32 v249, s75, 11
	v_writelane_b32 v249, s76, 12
	v_writelane_b32 v249, s77, 13
	v_writelane_b32 v249, s78, 14
	v_writelane_b32 v249, s79, 15
	v_writelane_b32 v249, s80, 16
	v_writelane_b32 v249, s81, 17
	v_writelane_b32 v249, s82, 18
	v_writelane_b32 v249, s83, 19
	v_writelane_b32 v249, s84, 20
	v_writelane_b32 v249, s85, 21
	v_writelane_b32 v249, s86, 22
	v_writelane_b32 v249, s87, 23
	v_writelane_b32 v249, s88, 24
	v_writelane_b32 v249, s89, 25
	v_writelane_b32 v249, s90, 26
	v_writelane_b32 v249, s91, 27
	v_writelane_b32 v249, s92, 28
	v_writelane_b32 v249, s93, 29
	v_writelane_b32 v249, s94, 30
	v_writelane_b32 v249, s95, 31
	v_writelane_b32 v249, s96, 32
	v_writelane_b32 v249, s97, 33
	v_readlane_b32 s1, v250, 9
	v_readlane_b32 s86, v250, 10
	v_readlane_b32 s87, v250, 11
	s_sub_i32 s0, s2, 0x74
	s_lshl_b32 s0, s0, 3
	s_nop 1
	s_add_i32 s12, s0, s1
	s_add_i32 s12, s12, 0x17600
	s_movk_i32 s14, 0x460
	s_mov_b32 s100, 0x1aa80
	s_mov_b32 s101, 1
	s_branch .Lcv_entry
.Lcv_return:
	v_readlane_b32 s0, v248, 0
	v_readlane_b32 s1, v248, 1
	v_readlane_b32 s2, v248, 2
	v_readlane_b32 s3, v248, 3
	v_readlane_b32 s4, v248, 4
	v_readlane_b32 s5, v248, 5
	v_readlane_b32 s6, v248, 6
	v_readlane_b32 s7, v248, 7
	v_readlane_b32 s8, v248, 8
	v_readlane_b32 s9, v248, 9
	v_readlane_b32 s10, v248, 10
	v_readlane_b32 s11, v248, 11
	v_readlane_b32 s12, v248, 12
	v_readlane_b32 s13, v248, 13
	v_readlane_b32 s14, v248, 14
	v_readlane_b32 s15, v248, 15
	v_readlane_b32 s16, v248, 16
	v_readlane_b32 s17, v248, 17
	v_readlane_b32 s18, v248, 18
	v_readlane_b32 s19, v248, 19
	v_readlane_b32 s20, v248, 20
	v_readlane_b32 s21, v248, 21
	v_readlane_b32 s22, v248, 22
	v_readlane_b32 s23, v248, 23
	v_readlane_b32 s24, v248, 24
	v_readlane_b32 s25, v248, 25
	v_readlane_b32 s26, v248, 26
	v_readlane_b32 s27, v248, 27
	v_readlane_b32 s28, v248, 28
	v_readlane_b32 s29, v248, 29
	v_readlane_b32 s30, v248, 30
	v_readlane_b32 s31, v248, 31
	v_readlane_b32 s32, v248, 32
	v_readlane_b32 s33, v248, 33
	v_readlane_b32 s34, v248, 34
	v_readlane_b32 s35, v248, 35
	v_readlane_b32 s36, v248, 36
	v_readlane_b32 s37, v248, 37
	v_readlane_b32 s38, v248, 38
	v_readlane_b32 s39, v248, 39
	v_readlane_b32 s40, v248, 40
	v_readlane_b32 s41, v248, 41
	v_readlane_b32 s42, v248, 42
	v_readlane_b32 s43, v248, 43
	v_readlane_b32 s44, v248, 44
	v_readlane_b32 s45, v248, 45
	v_readlane_b32 s46, v248, 46
	v_readlane_b32 s47, v248, 47
	v_readlane_b32 s48, v248, 48
	v_readlane_b32 s49, v248, 49
	v_readlane_b32 s50, v248, 50
	v_readlane_b32 s51, v248, 51
	v_readlane_b32 s52, v248, 52
	v_readlane_b32 s53, v248, 53
	v_readlane_b32 s54, v248, 54
	v_readlane_b32 s55, v248, 55
	v_readlane_b32 s56, v248, 56
	v_readlane_b32 s57, v248, 57
	v_readlane_b32 s58, v248, 58
	v_readlane_b32 s59, v248, 59
	v_readlane_b32 s60, v248, 60
	v_readlane_b32 s61, v248, 61
	v_readlane_b32 s62, v248, 62
	v_readlane_b32 s63, v248, 63
	v_readlane_b32 s64, v249, 0
	v_readlane_b32 s65, v249, 1
	v_readlane_b32 s66, v249, 2
	v_readlane_b32 s67, v249, 3
	v_readlane_b32 s68, v249, 4
	v_readlane_b32 s69, v249, 5
	v_readlane_b32 s70, v249, 6
	v_readlane_b32 s71, v249, 7
	v_readlane_b32 s72, v249, 8
	v_readlane_b32 s73, v249, 9
	v_readlane_b32 s74, v249, 10
	v_readlane_b32 s75, v249, 11
	v_readlane_b32 s76, v249, 12
	v_readlane_b32 s77, v249, 13
	v_readlane_b32 s78, v249, 14
	v_readlane_b32 s79, v249, 15
	v_readlane_b32 s80, v249, 16
	v_readlane_b32 s81, v249, 17
	v_readlane_b32 s82, v249, 18
	v_readlane_b32 s83, v249, 19
	v_readlane_b32 s84, v249, 20
	v_readlane_b32 s85, v249, 21
	v_readlane_b32 s86, v249, 22
	v_readlane_b32 s87, v249, 23
	v_readlane_b32 s88, v249, 24
	v_readlane_b32 s89, v249, 25
	v_readlane_b32 s90, v249, 26
	v_readlane_b32 s91, v249, 27
	v_readlane_b32 s92, v249, 28
	v_readlane_b32 s93, v249, 29
	v_readlane_b32 s94, v249, 30
	v_readlane_b32 s95, v249, 31
	v_readlane_b32 s96, v249, 32
	v_readlane_b32 s97, v249, 33
	s_nop 7
